# plus NSA tile loop: K/V global loads prefetched 2 tiles ahead (parity-selected register sets)
# speedup vs baseline: 1.0106x; 1.0106x over previous
.LBB0_733:
	s_or_b64 exec, exec, s[4:5]
	s_add_i32 s74, 0, 0x1e310
	v_mul_f32_e32 v36, v1, v40
	v_mov_b32_e32 v1, s74
	s_waitcnt lgkmcnt(0)
	s_barrier
	ds_read_b32 v1, v1
	s_sub_i32 s0, s78, s2
	s_add_i32 s73, s0, s81
	s_add_i32 s73, s73, 1
	s_movk_i32 s0, 0x200
	s_waitcnt lgkmcnt(0)
	v_readfirstlane_b32 s2, v1
	s_bitcmp0_b32 s2, 8
	s_cselect_b32 s68, 0x100, s0
	s_lshl_b64 s[0:1], s[88:89], 11
	s_lshl_b32 s2, s2, 6
	v_ashrrev_i32_e32 v35, 31, v34
	s_and_b32 s88, s2, 0x3fc0
	v_lshl_add_u64 v[146:147], s[0:1], 0, v[34:35]
	v_readlane_b32 s0, v253, 32
	v_readlane_b32 s2, v253, 34
	v_readlane_b32 s3, v253, 35
	v_pk_mul_f32 v[142:143], v[36:37], v[4:5] op_sel_hi:[0,1]
	v_pk_mul_f32 v[144:145], v[36:37], v[2:3] op_sel_hi:[0,1]
	v_lshl_add_u64 v[2:3], v[146:147], 0, s[88:89]
	v_readlane_b32 s1, v253, 33
	v_mov_b64_e32 v[4:5], s[2:3]
	s_movk_i32 s2, 0x1e00
	v_mad_u64_u32 v[4:5], s[0:1], v2, s2, v[4:5]
	s_mov_b32 s69, 0
	v_mad_i32_i24 v5, v3, s2, v5
	v_lshl_add_u64 v[2:3], v[4:5], 0, s[68:69]
	v_lshlrev_b32_e32 v4, 4, v39
	v_mov_b32_e32 v5, v0
	v_lshl_add_u64 v[2:3], v[2:3], 0, v[4:5]
	s_mov_b64 s[0:1], 0x1900
	v_pk_mul_f32 v[140:141], v[36:37], v[6:7] op_sel_hi:[0,1]
	v_lshl_add_u64 v[6:7], v[2:3], 0, s[0:1]
	v_add_co_u32_e32 v2, vcc, s86, v2
	s_movk_i32 s0, 0x90
	s_nop 0
	v_addc_co_u32_e32 v3, vcc, 0, v3, vcc
	global_load_dwordx4 v[96:99], v[2:3], off offset:2304
	global_load_dwordx4 v[100:103], v[6:7], off offset:128
	v_mul_lo_u32 v1, v34, s0
	s_movk_i32 s0, 0xff72
	v_add_u32_e32 v1, 0, v1
	v_mul_lo_u32 v2, v34, s0
	v_mul_u32_u24_e32 v3, 0x440, v39
	v_pk_mul_f32 v[130:131], v[36:37], v[16:17] op_sel_hi:[0,1]
	v_pk_mul_f32 v[132:133], v[36:37], v[14:15] op_sel_hi:[0,1]
	v_pk_mul_f32 v[134:135], v[36:37], v[12:13] op_sel_hi:[0,1]
	v_pk_mul_f32 v[136:137], v[36:37], v[10:11] op_sel_hi:[0,1]
	v_pk_mul_f32 v[138:139], v[36:37], v[8:9] op_sel_hi:[0,1]
	v_pk_mul_f32 v[114:115], v[36:37], v[32:33] op_sel_hi:[0,1]
	v_pk_mul_f32 v[116:117], v[36:37], v[30:31] op_sel_hi:[0,1]
	v_pk_mul_f32 v[118:119], v[36:37], v[28:29] op_sel_hi:[0,1]
	v_pk_mul_f32 v[120:121], v[36:37], v[26:27] op_sel_hi:[0,1]
	v_pk_mul_f32 v[122:123], v[36:37], v[24:25] op_sel_hi:[0,1]
	v_pk_mul_f32 v[124:125], v[36:37], v[22:23] op_sel_hi:[0,1]
	v_pk_mul_f32 v[126:127], v[36:37], v[20:21] op_sel_hi:[0,1]
	v_pk_mul_f32 v[128:129], v[36:37], v[18:19] op_sel_hi:[0,1]
	v_add_u32_e32 v153, v1, v4
	v_add3_u32 v154, v1, v2, v3
	s_cmp_lt_i32 s73, 1
	v_readlane_b32 s4, v253, 36
	v_readlane_b32 s5, v253, 37
	v_readlane_b32 s6, v253, 38
	v_readlane_b32 s7, v253, 39
	v_readlane_b32 s8, v253, 40
	v_readlane_b32 s9, v253, 41
	v_readlane_b32 s10, v253, 42
	v_readlane_b32 s11, v253, 43
	v_readlane_b32 s12, v253, 44
	v_readlane_b32 s13, v253, 45
	v_readlane_b32 s14, v253, 46
	v_readlane_b32 s15, v253, 47
	s_waitcnt vmcnt(1)
	ds_write_b128 v153, v[96:99]
	s_waitcnt vmcnt(0)
	ds_write_b16 v154, v100 offset:18432
	ds_write_b16_d16_hi v154, v100 offset:18568
	ds_write_b16 v154, v101 offset:18704
	ds_write_b16_d16_hi v154, v101 offset:18840
	ds_write_b16 v154, v102 offset:18976
	ds_write_b16_d16_hi v154, v102 offset:19112
	ds_write_b16 v154, v103 offset:19248
	ds_write_b16_d16_hi v154, v103 offset:19384
	s_waitcnt lgkmcnt(0)
	s_barrier
	s_cbranch_scc1 .LBB0_852
	v_mul_f32_e32 v1, 0xbfb8aa3b, v105
	v_exp_f32_e32 v1, v1
	v_sub_u32_e32 v2, v68, v150
	v_writelane_b32 v254, s41, 25
	v_cmp_gt_i32_e64 s[0:1], 0, v2
	v_add_f32_e32 v1, 1.0, v1
	v_cmp_gt_i32_e64 s[2:3], 35, v2
	v_writelane_b32 v254, s0, 15
	v_rcp_f32_e32 v156, v1
	v_mov_b32_e32 v14, v0
	v_writelane_b32 v254, s1, 16
	v_writelane_b32 v254, s2, 17
	v_mov_b32_e32 v15, v0
	v_lshlrev_b32_e32 v16, 3, v39
	v_writelane_b32 v254, s3, 18
	v_cmp_gt_i32_e64 s[2:3], 8, v2
	v_sub_u32_e32 v155, v150, v67
	v_cmp_gt_i32_e64 s[86:87], 32, v2
	v_cmp_gt_i32_e64 s[94:95], 1, v2
	v_cmp_gt_i32_e64 s[82:83], 33, v2
	v_cmp_gt_i32_e64 s[92:93], 2, v2
	v_cmp_gt_i32_e64 s[96:97], 34, v2
	v_cmp_gt_i32_e64 s[0:1], 3, v2
	v_writelane_b32 v254, s2, 19
	v_cmp_gt_i32_e64 s[20:21], 40, v2
	v_cmp_gt_i32_e64 s[22:23], 9, v2
	v_cmp_gt_i32_e64 s[24:25], 41, v2
	v_cmp_gt_i32_e64 s[26:27], 10, v2
	v_cmp_gt_i32_e64 s[28:29], 42, v2
	v_cmp_gt_i32_e64 s[30:31], 11, v2
	v_cmp_gt_i32_e64 s[34:35], 43, v2
	v_cmp_gt_i32_e64 s[36:37], 16, v2
	v_cmp_gt_i32_e64 s[38:39], 48, v2
	v_cmp_gt_i32_e64 s[40:41], 17, v2
	v_cmp_gt_i32_e64 s[42:43], 49, v2
	v_cmp_gt_i32_e64 s[44:45], 18, v2
	v_cmp_gt_i32_e64 s[46:47], 50, v2
	v_cmp_gt_i32_e64 s[48:49], 19, v2
	v_cmp_gt_i32_e64 s[50:51], 51, v2
	v_cmp_gt_i32_e64 s[52:53], 24, v2
	v_cmp_gt_i32_e64 s[54:55], 56, v2
	v_cmp_gt_i32_e64 s[56:57], 25, v2
	v_cmp_gt_i32_e64 s[58:59], 57, v2
	v_cmp_gt_i32_e64 s[60:61], 26, v2
	v_cmp_gt_i32_e64 s[62:63], 58, v2
	v_cmp_gt_i32_e64 s[64:65], 27, v2
	v_cmp_gt_i32_e64 s[66:67], 59, v2
	v_mul_u32_u24_e32 v158, 0x88, v66
	v_mov_b32_e32 v1, v0
	v_mov_b32_e32 v2, v0
	v_mov_b32_e32 v3, v0
	v_mov_b32_e32 v4, v0
	v_mov_b32_e32 v5, v0
	v_mov_b32_e32 v6, v0
	v_mov_b32_e32 v7, v0
	v_mov_b32_e32 v8, v0
	v_mov_b32_e32 v9, v0
	v_mov_b32_e32 v10, v0
	v_mov_b32_e32 v11, v0
	v_mov_b32_e32 v12, v0
	v_mov_b32_e32 v13, v0
	v_mov_b64_e32 v[78:79], v[14:15]
	v_mov_b64_e32 v[62:63], v[14:15]
	v_mul_u32_u24_e32 v157, 0x90, v37
	v_writelane_b32 v254, s3, 20
	v_mul_u32_u24_e32 v159, 0x88, v37
	v_mov_b32_e32 v161, 0xf149f2ca
	v_mov_b32_e32 v166, 0
	v_lshlrev_b32_e32 v104, 1, v16
	v_mov_b64_e32 v[76:77], v[12:13]
	v_mov_b64_e32 v[74:75], v[10:11]
	v_mov_b64_e32 v[72:73], v[8:9]
	v_mov_b64_e32 v[70:71], v[6:7]
	v_mov_b64_e32 v[68:69], v[4:5]
	v_mov_b64_e32 v[66:67], v[2:3]
	v_mov_b64_e32 v[64:65], v[0:1]
	v_mov_b64_e32 v[60:61], v[12:13]
	v_mov_b64_e32 v[58:59], v[10:11]
	v_mov_b64_e32 v[56:57], v[8:9]
	v_mov_b64_e32 v[54:55], v[6:7]
	v_mov_b64_e32 v[52:53], v[4:5]
	v_mov_b64_e32 v[50:51], v[2:3]
	v_mov_b64_e32 v[48:49], v[0:1]
	s_cmp_lt_i32 s73, 2
	s_cbranch_scc1 .Lnsa_pf_skip
	v_mov_b32_e32 v1, s74
	ds_read_b32 v1, v1 offset:4
	s_movk_i32 s4, 0x200
	s_mov_b32 s91, s89
	v_readlane_b32 s6, v253, 34
	s_waitcnt lgkmcnt(0)
	v_readfirstlane_b32 s68, v1
	s_bitcmp0_b32 s68, 8
	s_cselect_b32 s88, 0x100, s4
	s_lshl_b32 s68, s68, 6
	v_readlane_b32 s7, v253, 35
	s_and_b32 s90, s68, 0x3fc0
	v_lshl_add_u64 v[4:5], v[146:147], 0, s[90:91]
	v_mov_b64_e32 v[2:3], s[6:7]
	s_movk_i32 s4, 0x1e00
	v_mad_u64_u32 v[2:3], s[90:91], v4, s4, v[2:3]
	v_mad_i32_i24 v3, v5, s4, v3
	v_lshl_add_u64 v[2:3], v[2:3], 0, s[88:89]
	v_mov_b32_e32 v105, v0
	v_lshl_add_u64 v[2:3], v[2:3], 0, v[104:105]
	s_mov_b64 s[4:5], 0x1900
	v_lshl_add_u64 v[4:5], v[2:3], 0, s[4:5]
	v_add_co_u32_e32 v2, vcc, 0x1000, v2
	s_nop 1
	v_addc_co_u32_e32 v3, vcc, 0, v3, vcc
	global_load_dwordx4 v[206:209], v[2:3], off offset:2304
	global_load_dwordx4 v[210:213], v[4:5], off offset:128
.Lnsa_pf_skip:
.LBB0_735:
	s_add_i32 s84, s69, 1
	s_cmp_lt_i32 s84, s73
	s_cselect_b64 s[70:71], -1, 0
	s_cmp_ge_i32 s84, s73
	s_cselect_b64 s[2:3], -1, 0
	s_add_i32 s4, s69, 2
	s_cmp_ge_i32 s4, s73
	s_cbranch_scc1 .LBB0_737
	v_mov_b32_e32 v1, s74
	ds_read_b32 v1, v1 offset:8
	v_readlane_b32 s4, v253, 32
	s_movk_i32 s4, 0x200
	s_mov_b32 s91, s89
	v_readlane_b32 s6, v253, 34
	s_waitcnt lgkmcnt(0)
	v_readfirstlane_b32 s68, v1
	s_bitcmp0_b32 s68, 8
	s_cselect_b32 s88, 0x100, s4
	s_lshl_b32 s68, s68, 6
	v_readlane_b32 s7, v253, 35
	s_and_b32 s90, s68, 0x3fc0
	v_lshl_add_u64 v[4:5], v[146:147], 0, s[90:91]
	v_mov_b64_e32 v[2:3], s[6:7]
	s_movk_i32 s4, 0x1e00
	v_mad_u64_u32 v[2:3], s[90:91], v4, s4, v[2:3]
	v_mad_i32_i24 v3, v5, s4, v3
	v_readlane_b32 s5, v253, 33
	v_lshl_add_u64 v[2:3], v[2:3], 0, s[88:89]
	v_mov_b32_e32 v105, v0
	v_lshl_add_u64 v[2:3], v[2:3], 0, v[104:105]
	s_mov_b64 s[4:5], 0x1900
	v_lshl_add_u64 v[4:5], v[2:3], 0, s[4:5]
	v_add_co_u32_e32 v2, vcc, 0x1000, v2
	v_readlane_b32 s8, v253, 36
	s_nop 0
	v_addc_co_u32_e32 v3, vcc, 0, v3, vcc
	s_bitcmp1_b32 s69, 0
	s_cbranch_scc1 .Lnsa_ld_odd
	global_load_dwordx4 v[96:99], v[2:3], off offset:2304
	global_load_dwordx4 v[100:103], v[4:5], off offset:128
	s_branch .Lnsa_ld_done
.Lnsa_ld_odd:
	global_load_dwordx4 v[206:209], v[2:3], off offset:2304
	global_load_dwordx4 v[210:213], v[4:5], off offset:128
.Lnsa_ld_done:
	v_readlane_b32 s9, v253, 37
	v_readlane_b32 s10, v253, 38
	v_readlane_b32 s11, v253, 39
	v_readlane_b32 s12, v253, 40
	v_readlane_b32 s13, v253, 41
	v_readlane_b32 s14, v253, 42
	v_readlane_b32 s15, v253, 43
	v_readlane_b32 s16, v253, 44
	v_readlane_b32 s17, v253, 45
	v_readlane_b32 s18, v253, 46
	v_readlane_b32 s19, v253, 47

.LBB0_841:
	s_and_b32 s68, s84, 1
	s_mul_i32 s69, s68, 0x2400
	v_add_u32_e32 v1, s69, v153
	s_mulk_i32 s68, 0x2200
	s_add_i32 s69, s84, 1
	s_cmp_lt_i32 s69, s73
	s_cbranch_scc1 .Lnsa_w2
	s_waitcnt vmcnt(0)
	s_branch .Lnsa_wd
.Lnsa_w2:
	s_waitcnt vmcnt(2)
.Lnsa_wd:
	s_bitcmp1_b32 s84, 0
	s_cbranch_scc1 .Lnsa_sw_B
	ds_write_b128 v1, v[96:99]
	v_add_u32_e32 v1, s68, v154
	ds_write_b16 v1, v100 offset:18432
	ds_write_b16_d16_hi v1, v100 offset:18568
	ds_write_b16 v1, v101 offset:18704
	ds_write_b16_d16_hi v1, v101 offset:18840
	ds_write_b16 v1, v102 offset:18976
	ds_write_b16_d16_hi v1, v102 offset:19112
	ds_write_b16 v1, v103 offset:19248
	ds_write_b16_d16_hi v1, v103 offset:19384
	s_branch .LBB0_842
.Lnsa_sw_B:
	ds_write_b128 v1, v[206:209]
	v_add_u32_e32 v1, s68, v154
	ds_write_b16 v1, v210 offset:18432
	ds_write_b16_d16_hi v1, v210 offset:18568
	ds_write_b16 v1, v211 offset:18704
	ds_write_b16_d16_hi v1, v211 offset:18840
	ds_write_b16 v1, v212 offset:18976
	ds_write_b16_d16_hi v1, v212 offset:19112
	ds_write_b16 v1, v213 offset:19248
	ds_write_b16_d16_hi v1, v213 offset:19384
